# attention A: K fragments requested one slice ahead in the even step; exp2 of the first score block moved into the last P.V MFMA shadow (rare rescale path recomputes)
# baseline (speedup 1.0000x reference)
; template <int OFF> __device__ __forceinline__ s16x4 tr_read(int vb) { s16x4 r; asm volatile("ds_read_b64_tr_b16 %0, %1 offset:%2" : "=&v"(r) : "v"(vb), "i"(OFF) : "memory"); return r; }
; __device__ __forceinline__ void finishSM(f32x16& p0, f32x16& p1, float alpha, float& l_reg, bf16x8& pa0, bf16x8& pa1, bf16x8& pa2, bf16x8& pa3) {
; #pragma unroll
;   for (int r = 0; r < 16; ++r) p1[r] = __builtin_amdgcn_exp2f(p1[r]);
;   float ps = 0;
; #pragma unroll
;   for (int r = 0; r < 16; ++r) ps += p0[r];
; #pragma unroll
;   for (int r = 0; r < 16; ++r) ps += p1[r];
;   { auto rr = __builtin_amdgcn_permlane32_swap(__float_as_uint(ps), __float_as_uint(ps), false, false);
;     ps = __uint_as_float(rr[0]) + __uint_as_float(rr[1]); }
;   l_reg = l_reg * alpha + ps;
;     ...
;   ATT_PKN(p0, 0, pa0); ATT_PKN(p0, 8, pa1); ATT_PKN(p1, 0, pa2); ATT_PKN(p1, 8, pa3);
;     ...
; }
; __device__ __forceinline__ void qkt(f32x16& p0, f32x16& p1, const bf16* Ks, const bf16x8* qr, int r32, int hi, int mp, const f32x16& negm) {
; #pragma unroll
;   for (int d0 = 0; d0 < 4; ++d0) { int cb = ((mp * 4 + d0) * 16 + hi * 8) * 2;
;     bf16x8 b0 = *reinterpret_cast<const bf16x8*>((const char*)Ks + KSWZ(r32, cb));
;     bf16x8 b1 = *reinterpret_cast<const bf16x8*>((const char*)Ks + KSWZ(32 + r32, cb));
;     if (d0 == 0) { p0 = __builtin_amdgcn_mfma_f32_32x32x16_bf16(b0, qr[0], negm, 0, 0, 0); p1 = __builtin_amdgcn_mfma_f32_32x32x16_bf16(b1, qr[0], negm, 0, 0, 0); }
;     else { p0 = __builtin_amdgcn_mfma_f32_32x32x16_bf16(b0, qr[d0], p0, 0, 0, 0); p1 = __builtin_amdgcn_mfma_f32_32x32x16_bf16(b1, qr[d0], p1, 0, 0, 0); } }
; }
; __device__ __forceinline__ int v_st(int k, int c) { const int kk = k; return ((kk >> 3) * 4 + (c >> 5)) * 512 + ((kk & 7) * 32 + (c & 31)) * 2; }
; template <int D0> __device__ __forceinline__ void pv_one(f32x16& od, int vb, bf16x8 pa0, bf16x8 pa1, bf16x8 pa2, bf16x8 pa3) {
;   const s16x4 l0 = tr_read<v_rd_off(D0, 0, 0)>(vb), h0 = tr_read<v_rd_off(D0, 0, 1)>(vb), l1 = tr_read<v_rd_off(D0, 1, 0)>(vb), h1 = tr_read<v_rd_off(D0, 1, 1)>(vb);
;   const s16x4 l2 = tr_read<v_rd_off(D0, 2, 0)>(vb), h2 = tr_read<v_rd_off(D0, 2, 1)>(vb), l3 = tr_read<v_rd_off(D0, 3, 0)>(vb), h3 = tr_read<v_rd_off(D0, 3, 1)>(vb);
.LBB0_197:
	s_add_i32 s10, s39, 0
	v_add_u32_e32 v112, s10, v202
	ds_read_b128 v[236:239], v112 offset:24576
	ds_read_b128 v[112:115], v112 offset:16384
	v_add_u32_e32 v208, s10, v201
	ds_read_b128 v[68:71], v208 offset:24576
	ds_read_b128 v[72:75], v208 offset:16384
	v_add_u32_e32 v208, s10, v199
	v_exp_f32_e32 v210, v96
	v_add_f32_e32 v96, 0, v172
	v_add_f32_e32 v96, v174, v96
	s_waitcnt lgkmcnt(2)
	v_mfma_f32_32x32x16_bf16 v[128:143], v[112:115], v[158:161], v[80:95]
	v_mov_b64_e32 v[126:127], v[94:95]
	v_mov_b64_e32 v[124:125], v[92:93]
	v_mov_b64_e32 v[122:123], v[90:91]
	v_mov_b64_e32 v[120:121], v[88:89]
	v_mov_b64_e32 v[118:119], v[86:87]
	v_mov_b64_e32 v[116:117], v[84:85]
	v_mov_b64_e32 v[114:115], v[82:83]
	v_mov_b64_e32 v[112:113], v[80:81]
	v_add_f32_e32 v96, v175, v96
	v_add_f32_e32 v96, v211, v96
	v_mfma_f32_32x32x16_bf16 v[112:127], v[236:239], v[158:161], v[112:127]
	ds_read_b128 v[236:239], v208 offset:24576
	ds_read_b128 v[240:243], v208 offset:16384
	v_add_u32_e32 v208, s10, v183
	v_add_f32_e32 v96, v212, v96
	v_add_f32_e32 v96, v215, v96
	v_add_f32_e32 v96, v216, v96
	v_add_f32_e32 v96, v233, v96
	v_add_f32_e32 v96, v173, v96
	s_waitcnt lgkmcnt(2)
	v_mfma_f32_32x32x16_bf16 v[112:127], v[68:71], v[154:157], v[112:127]
	v_add_f32_e32 v96, v176, v96
	v_add_f32_e32 v96, v177, v96
	v_add_f32_e32 v96, v213, v96
	v_add_f32_e32 v96, v214, v96
	v_exp_f32_e32 v235, v97
	v_add_f32_e32 v96, v217, v96
	v_add_f32_e32 v96, v232, v96
	v_mfma_f32_32x32x16_bf16 v[128:143], v[72:75], v[154:157], v[128:143]
	ds_read_b128 v[68:71], v208 offset:24576
	ds_read_b128 v[72:75], v208 offset:16384
	v_add_f32_e32 v96, v234, v96
	v_add_f32_e32 v96, v210, v96
	v_add_f32_e32 v96, v235, v96
	v_exp_f32_e32 v244, v106
	v_exp_f32_e32 v245, v107
	s_waitcnt lgkmcnt(2)
	v_mfma_f32_32x32x16_bf16 v[112:127], v[236:239], v[150:153], v[112:127]
	v_exp_f32_e32 v246, v108
	v_exp_f32_e32 v247, v109
	v_exp_f32_e32 v248, v110
	v_exp_f32_e32 v111, v111
	v_cvt_pk_bf16_f32 v97, v175, v211
	v_cvt_pk_bf16_f32 v109, v244, v245
	v_cvt_pk_bf16_f32 v110, v246, v247
	v_mfma_f32_32x32x16_bf16 v[128:143], v[240:243], v[150:153], v[128:143]
	s_waitcnt lgkmcnt(0)
	v_mfma_f32_32x32x16_bf16 v[112:127], v[68:71], v[146:149], v[112:127]
	v_exp_f32_e32 v236, v98
	v_exp_f32_e32 v237, v99
	v_exp_f32_e32 v238, v100
	v_exp_f32_e32 v239, v101
	v_add_f32_e32 v96, v236, v96
	v_add_f32_e32 v96, v237, v96
	v_add_f32_e32 v96, v238, v96
	v_mfma_f32_32x32x16_bf16 v[128:143], v[72:75], v[146:149], v[128:143]
	v_exp_f32_e32 v240, v102
	v_exp_f32_e32 v241, v103
	v_exp_f32_e32 v242, v104
	v_exp_f32_e32 v243, v105
	v_add_f32_e32 v96, v239, v96
	v_add_f32_e32 v96, v240, v96
	v_add_f32_e32 v96, v241, v96
	v_add_f32_e32 v96, v242, v96
	v_add_f32_e32 v96, v243, v96
	v_add_f32_e32 v96, v244, v96
	v_add_f32_e32 v96, v245, v96
	v_add_f32_e32 v96, v246, v96
	v_add_f32_e32 v96, v247, v96
	v_add_f32_e32 v96, v248, v96
	v_add_f32_e32 v208, v111, v96
	v_mov_b32_e32 v209, v208
	s_nop 1
	v_permlane32_swap_b32_e32 v208, v209
	v_cvt_pk_bf16_f32 v96, v172, v174
	v_cvt_pk_bf16_f32 v98, v212, v215
	v_cvt_pk_bf16_f32 v99, v216, v233
	v_cvt_pk_bf16_f32 v100, v173, v176
	v_cvt_pk_bf16_f32 v101, v177, v213
	v_cvt_pk_bf16_f32 v102, v214, v217
	v_cvt_pk_bf16_f32 v103, v232, v234
	v_cvt_pk_bf16_f32 v104, v210, v235
	v_cvt_pk_bf16_f32 v105, v236, v237
	v_cvt_pk_bf16_f32 v106, v238, v239
	v_cvt_pk_bf16_f32 v107, v240, v241
	v_cvt_pk_bf16_f32 v108, v242, v243
	v_cvt_pk_bf16_f32 v111, v248, v111
	v_add_u32_e32 v240, s48, v205
	ds_read_b64_tr_b16 v[210:211], v240 offset:0
	ds_read_b64_tr_b16 v[212:213], v240 offset:0x800
	ds_read_b64_tr_b16 v[214:215], v240 offset:0x1000
	ds_read_b64_tr_b16 v[216:217], v240 offset:0x1800
	ds_read_b64_tr_b16 v[232:233], v240 offset:0x2000
	ds_read_b64_tr_b16 v[234:235], v240 offset:0x2800
	ds_read_b64_tr_b16 v[236:237], v240 offset:0x3000
	ds_read_b64_tr_b16 v[238:239], v240 offset:0x3800
	v_lshl_add_u64 v[174:175], s[50:51], 0, v[168:169]
	s_add_i32 s12, s21, s56
	v_lshl_add_u64 v[172:173], v[174:175], 0, s[36:37]
	s_add_i32 m0, s12, 0x4000
	s_mov_b64 s[10:11], 0x4030000
	global_load_lds_dwordx4 v[172:173], off
	v_lshl_add_u64 v[172:173], s[50:51], 0, v[188:189]
	v_lshl_add_u64 v[176:177], v[172:173], 0, s[10:11]
	s_mov_b32 m0, s12
	s_mov_b64 s[10:11], 0x4030080
	global_load_lds_dwordx4 v[176:177], off
	v_lshl_add_u64 v[176:177], s[50:51], 0, v[170:171]
	v_lshl_add_u64 v[66:67], v[176:177], 0, s[36:37]
	s_add_i32 m0, s12, 0x4400
	s_nop 0
	global_load_lds_dwordx4 v[66:67], off
	v_lshl_add_u64 v[66:67], v[172:173], 0, s[10:11]
	s_add_i32 m0, s12, 0x400
	s_nop 0
	global_load_lds_dwordx4 v[66:67], off
	s_waitcnt lgkmcnt(0)
; #define SBAR() __builtin_amdgcn_sched_barrier(0)
; template <int OFF> __device__ __forceinline__ s16x4 tr_read(int vb) { s16x4 r; asm volatile("ds_read_b64_tr_b16 %0, %1 offset:%2" : "=&v"(r) : "v"(vb), "i"(OFF) : "memory"); return r; }
; template <bool FIRST> __device__ __forceinline__ void partialSM(f32x16& p0, f32x16& p1, float& m_reg, f32x16& negm, float& alpha) {
;   float pmax = p0[0];
; #pragma unroll
;   for (int r = 1; r < 16; ++r) pmax = fmaxf(pmax, p0[r]);
; #pragma unroll
;   for (int r = 0; r < 16; ++r) pmax = fmaxf(pmax, p1[r]);
;   { auto rr = __builtin_amdgcn_permlane32_swap(__float_as_uint(pmax), __float_as_uint(pmax), false, false);
;     pmax = fmaxf(__uint_as_float(rr[0]), __uint_as_float(rr[1])); }
;   alpha = 1.f;
;   if (FIRST || __builtin_expect(__any(pmax > THR), 0)) { const float dl = FIRST ? pmax : fmaxf(pmax, 0.f); m_reg += dl; if (!FIRST) alpha = __builtin_amdgcn_exp2f(-dl);
; #pragma unroll
;     for (int r = 0; r < 16; ++r) { p0[r] -= dl; p1[r] -= dl; }
; #pragma unroll
;     for (int r = 0; r < 16; ++r) negm[r] = -m_reg; }
; #pragma unroll
;   for (int r = 0; r < 16; ++r) p0[r] = __builtin_amdgcn_exp2f(p0[r]);
; template <int D0> __device__ __forceinline__ void pv_one(f32x16& od, int vb, bf16x8 pa0, bf16x8 pa1, bf16x8 pa2, bf16x8 pa3) {
;   const s16x4 l0 = tr_read<v_rd_off(D0, 0, 0)>(vb), h0 = tr_read<v_rd_off(D0, 0, 1)>(vb), l1 = tr_read<v_rd_off(D0, 1, 0)>(vb), h1 = tr_read<v_rd_off(D0, 1, 1)>(vb);
;   const s16x4 l2 = tr_read<v_rd_off(D0, 2, 0)>(vb), h2 = tr_read<v_rd_off(D0, 2, 1)>(vb), l3 = tr_read<v_rd_off(D0, 3, 0)>(vb), h3 = tr_read<v_rd_off(D0, 3, 1)>(vb);
;   asm volatile("s_waitcnt lgkmcnt(0)" ::: "memory"); SBAR();
;   od = __builtin_amdgcn_mfma_f32_32x32x16_bf16(pa0, ATT_PK(l0, h0), od, 0, 0, 0);
;   od = __builtin_amdgcn_mfma_f32_32x32x16_bf16(pa1, ATT_PK(l1, h1), od, 0, 0, 0);
;   od = __builtin_amdgcn_mfma_f32_32x32x16_bf16(pa2, ATT_PK(l2, h2), od, 0, 0, 0);
;   od = __builtin_amdgcn_mfma_f32_32x32x16_bf16(pa3, ATT_PK(l3, h3), od, 0, 0, 0);
; }
; __device__ __forceinline__ void pv_d0(f32x16* o, int vb, bf16x8 pa0, bf16x8 pa1, bf16x8 pa2, bf16x8 pa3) {
;   pv_one<0>(o[0], vb, pa0, pa1, pa2, pa3); pv_one<1>(o[1], vb, pa0, pa1, pa2, pa3); pv_one<2>(o[2], vb, pa0, pa1, pa2, pa3); pv_one<3>(o[3], vb, pa0, pa1, pa2, pa3);
; }
	s_nop 0
	v_mfma_f32_32x32x16_bf16 v[0:15], v[96:99], v[210:213], v[0:15]
	ds_read_b64_tr_b16 v[210:211], v240 offset:0x200
	ds_read_b64_tr_b16 v[212:213], v240 offset:0xa00
	v_mfma_f32_32x32x16_bf16 v[0:15], v[100:103], v[214:217], v[0:15]
	ds_read_b64_tr_b16 v[214:215], v240 offset:0x1200
	ds_read_b64_tr_b16 v[216:217], v240 offset:0x1a00
	v_mfma_f32_32x32x16_bf16 v[0:15], v[104:107], v[232:235], v[0:15]
	ds_read_b64_tr_b16 v[232:233], v240 offset:0x2200
	ds_read_b64_tr_b16 v[234:235], v240 offset:0x2a00
	v_mfma_f32_32x32x16_bf16 v[0:15], v[108:111], v[236:239], v[0:15]
	ds_read_b64_tr_b16 v[236:237], v240 offset:0x3200
	ds_read_b64_tr_b16 v[238:239], v240 offset:0x3a00
	s_waitcnt lgkmcnt(0)
	v_mfma_f32_32x32x16_bf16 v[48:63], v[96:99], v[210:213], v[48:63]
	ds_read_b64_tr_b16 v[210:211], v240 offset:0x400
	ds_read_b64_tr_b16 v[212:213], v240 offset:0xc00
	v_mfma_f32_32x32x16_bf16 v[48:63], v[100:103], v[214:217], v[48:63]
	ds_read_b64_tr_b16 v[214:215], v240 offset:0x1400
	ds_read_b64_tr_b16 v[216:217], v240 offset:0x1c00
	v_mfma_f32_32x32x16_bf16 v[48:63], v[104:107], v[232:235], v[48:63]
	ds_read_b64_tr_b16 v[232:233], v240 offset:0x2400
	ds_read_b64_tr_b16 v[234:235], v240 offset:0x2c00
	v_mfma_f32_32x32x16_bf16 v[48:63], v[108:111], v[236:239], v[48:63]
	ds_read_b64_tr_b16 v[236:237], v240 offset:0x3400
	ds_read_b64_tr_b16 v[238:239], v240 offset:0x3c00
	s_waitcnt lgkmcnt(0)
	v_mfma_f32_32x32x16_bf16 v[32:47], v[96:99], v[210:213], v[32:47]
	ds_read_b64_tr_b16 v[210:211], v240 offset:0x600
	ds_read_b64_tr_b16 v[212:213], v240 offset:0xe00
	v_mfma_f32_32x32x16_bf16 v[32:47], v[100:103], v[214:217], v[32:47]
	ds_read_b64_tr_b16 v[214:215], v240 offset:0x1600
	ds_read_b64_tr_b16 v[216:217], v240 offset:0x1e00
	v_mfma_f32_32x32x16_bf16 v[32:47], v[104:107], v[232:235], v[32:47]
	ds_read_b64_tr_b16 v[232:233], v240 offset:0x2600
	ds_read_b64_tr_b16 v[234:235], v240 offset:0x2e00
	v_mfma_f32_32x32x16_bf16 v[32:47], v[108:111], v[236:239], v[32:47]
	ds_read_b64_tr_b16 v[236:237], v240 offset:0x3600
	ds_read_b64_tr_b16 v[238:239], v240 offset:0x3e00
	s_waitcnt lgkmcnt(0)
	v_mfma_f32_32x32x16_bf16 v[16:31], v[96:99], v[210:213], v[16:31]
	v_exp_f32_e32 v211, v128
	v_exp_f32_e32 v213, v129
	v_exp_f32_e32 v212, v136
	v_max_f32_e32 v96, v129, v129
	v_max_f32_e32 v97, v128, v128
	v_max_f32_e32 v96, v97, v96
	v_max3_f32 v96, v96, v130, v131
	v_max3_f32 v96, v96, v132, v133
	v_max3_f32 v96, v96, v134, v135
	v_max3_f32 v96, v96, v136, v137
	v_mfma_f32_32x32x16_bf16 v[16:31], v[100:103], v[214:217], v[16:31]
	v_exp_f32_e32 v214, v130
	v_exp_f32_e32 v217, v131
	v_exp_f32_e32 v215, v137
	v_exp_f32_e32 v216, v138
	v_max3_f32 v96, v96, v138, v139
	v_max3_f32 v96, v96, v140, v141
	v_max3_f32 v96, v96, v142, v143
	v_max3_f32 v96, v96, v112, v113
	v_max3_f32 v96, v96, v114, v115
	v_max3_f32 v96, v96, v116, v117
	v_max3_f32 v96, v96, v118, v119
	v_mfma_f32_32x32x16_bf16 v[16:31], v[104:107], v[232:235], v[16:31]
	v_exp_f32_e32 v232, v132
	v_exp_f32_e32 v235, v133
	v_exp_f32_e32 v233, v139
	v_exp_f32_e32 v234, v140
	v_max3_f32 v96, v96, v120, v121
	v_max3_f32 v96, v96, v122, v123
	v_max3_f32 v96, v96, v124, v125
	v_max3_f32 v96, v96, v126, v127
	v_mov_b32_e32 v97, v96
	s_nop 1
	v_permlane32_swap_b32_e32 v96, v97
	v_mfma_f32_32x32x16_bf16 v[16:31], v[108:111], v[236:239], v[16:31]
	v_exp_f32_e32 v236, v134
	v_exp_f32_e32 v239, v135
	v_exp_f32_e32 v237, v141
	v_exp_f32_e32 v238, v142
	v_exp_f32_e32 v240, v143
	v_max_f32_e32 v97, v97, v97
	v_max_f32_e32 v96, v96, v96
	v_max_f32_e32 v96, v96, v97
	v_cmp_lt_f32_e32 vcc, s19, v96
	s_mov_b32 s98, 0
	s_cbranch_vccnz .LBB0_215
	v_mov_b64_e32 v[64:65], v[80:81]
	v_mov_b64_e32 v[66:67], v[82:83]
	v_mov_b64_e32 v[68:69], v[84:85]
	v_mov_b64_e32 v[70:71], v[86:87]
	v_mov_b64_e32 v[72:73], v[88:89]
	v_mov_b64_e32 v[74:75], v[90:91]
	v_mov_b64_e32 v[76:77], v[92:93]
	v_mov_b64_e32 v[78:79], v[94:95]
	v_mov_b32_e32 v210, 1.0
	v_cmp_gt_f32_e32 vcc, 1.0, v210
	s_cbranch_vccz .LBB0_202

; template <bool FIRST> __device__ __forceinline__ void partialSM(f32x16& p0, f32x16& p1, float& m_reg, f32x16& negm, float& alpha) {
;     ...
;   for (int r = 0; r < 16; ++r) p0[r] = __builtin_amdgcn_exp2f(p0[r]);
; }
; __device__ __forceinline__ void finishSM(f32x16& p0, f32x16& p1, float alpha, float& l_reg, bf16x8& pa0, bf16x8& pa1, bf16x8& pa2, bf16x8& pa3) {
; #pragma unroll
;   for (int r = 0; r < 16; ++r) p1[r] = __builtin_amdgcn_exp2f(p1[r]);
;   float ps = 0;
; #pragma unroll
;   for (int r = 0; r < 16; ++r) ps += p0[r];
; #pragma unroll
;   for (int r = 0; r < 16; ++r) ps += p1[r];
;   { auto rr = __builtin_amdgcn_permlane32_swap(__float_as_uint(ps), __float_as_uint(ps), false, false);
;     ps = __uint_as_float(rr[0]) + __uint_as_float(rr[1]); }
;   l_reg = l_reg * alpha + ps;
;     ...
;   ATT_PKN(p0, 0, pa0); ATT_PKN(p0, 8, pa1); ATT_PKN(p1, 0, pa2); ATT_PKN(p1, 8, pa3);
;     ...
; }
; __device__ __forceinline__ void qkt(f32x16& p0, f32x16& p1, const bf16* Ks, const bf16x8* qr, int r32, int hi, int mp, const f32x16& negm) {
; #pragma unroll
;   for (int d0 = 0; d0 < 4; ++d0) { int cb = ((mp * 4 + d0) * 16 + hi * 8) * 2;
;     bf16x8 b0 = *reinterpret_cast<const bf16x8*>((const char*)Ks + KSWZ(r32, cb));
;     bf16x8 b1 = *reinterpret_cast<const bf16x8*>((const char*)Ks + KSWZ(32 + r32, cb));
;     if (d0 == 0) { p0 = __builtin_amdgcn_mfma_f32_32x32x16_bf16(b0, qr[0], negm, 0, 0, 0); p1 = __builtin_amdgcn_mfma_f32_32x32x16_bf16(b1, qr[0], negm, 0, 0, 0); }
;     else { p0 = __builtin_amdgcn_mfma_f32_32x32x16_bf16(b0, qr[d0], p0, 0, 0, 0); p1 = __builtin_amdgcn_mfma_f32_32x32x16_bf16(b1, qr[d0], p1, 0, 0, 0); } }
; }
; __device__ __forceinline__ int v_st(int k, int c) { const int kk = k; return ((kk >> 3) * 4 + (c >> 5)) * 512 + ((kk & 7) * 32 + (c & 31)) * 2; }
; template <int D0> __device__ __forceinline__ void pv_one(f32x16& od, int vb, bf16x8 pa0, bf16x8 pa1, bf16x8 pa2, bf16x8 pa3) {
;   const s16x4 l0 = tr_read<v_rd_off(D0, 0, 0)>(vb), h0 = tr_read<v_rd_off(D0, 0, 1)>(vb), l1 = tr_read<v_rd_off(D0, 1, 0)>(vb), h1 = tr_read<v_rd_off(D0, 1, 1)>(vb);
;   const s16x4 l2 = tr_read<v_rd_off(D0, 2, 0)>(vb), h2 = tr_read<v_rd_off(D0, 2, 1)>(vb), l3 = tr_read<v_rd_off(D0, 3, 0)>(vb), h3 = tr_read<v_rd_off(D0, 3, 1)>(vb);
.LBB0_202:
	s_cmp_lg_u32 s98, 0
	s_cbranch_scc0 .Lexp1_done
	v_exp_f32_e32 v211, v128
	v_exp_f32_e32 v213, v129
	v_exp_f32_e32 v214, v130
	v_exp_f32_e32 v217, v131
	v_exp_f32_e32 v232, v132
	v_exp_f32_e32 v235, v133
	v_exp_f32_e32 v236, v134
	v_exp_f32_e32 v239, v135
	v_exp_f32_e32 v212, v136
	v_exp_f32_e32 v215, v137
	v_exp_f32_e32 v216, v138
	v_exp_f32_e32 v233, v139
	v_exp_f32_e32 v234, v140
	v_exp_f32_e32 v237, v141
	v_exp_f32_e32 v238, v142
	v_exp_f32_e32 v240, v143
.Lexp1_done:
	s_waitcnt vmcnt(4) lgkmcnt(0)
	s_barrier
	s_add_i32 s10, s39, 0x8000
	s_and_b32 s48, s10, 0x1ffff
	s_add_i32 s10, s48, 0
	v_add_u32_e32 v96, s10, v202
	ds_read_b128 v[242:245], v96 offset:24576
	ds_read_b128 v[96:99], v96 offset:16384
	v_add_u32_e32 v241, s10, v201
	v_exp_f32_e32 v112, v112
	v_exp_f32_e32 v115, v115
	v_exp_f32_e32 v116, v116
	s_waitcnt lgkmcnt(0)
	v_mfma_f32_32x32x16_bf16 v[128:143], v[96:99], v[158:161], v[64:79]
	v_exp_f32_e32 v117, v117
	v_exp_f32_e32 v118, v118
	v_mfma_f32_32x32x16_bf16 v[96:111], v[242:245], v[158:161], v[64:79]
	ds_read_b128 v[242:245], v241 offset:24576
	ds_read_b128 v[246:249], v241 offset:16384
	v_add_u32_e32 v241, s10, v199
	s_waitcnt lgkmcnt(0)
	v_mfma_f32_32x32x16_bf16 v[128:143], v[246:249], v[154:157], v[128:143]
	v_mfma_f32_32x32x16_bf16 v[96:111], v[242:245], v[154:157], v[96:111]
	ds_read_b128 v[242:245], v241 offset:24576
	ds_read_b128 v[246:249], v241 offset:16384
	v_add_u32_e32 v241, s10, v183
	s_waitcnt lgkmcnt(0)
	v_mfma_f32_32x32x16_bf16 v[128:143], v[246:249], v[150:153], v[128:143]
	v_mfma_f32_32x32x16_bf16 v[96:111], v[242:245], v[150:153], v[96:111]
	ds_read_b128 v[242:245], v241 offset:24576
	ds_read_b128 v[246:249], v241 offset:16384
	v_exp_f32_e32 v241, v113
	v_add_f32_e32 v113, 0, v211
	v_add_f32_e32 v113, v213, v113
	v_add_f32_e32 v113, v214, v113
	v_add_f32_e32 v113, v217, v113
	v_add_f32_e32 v113, v232, v113
	v_add_f32_e32 v113, v235, v113
	v_add_f32_e32 v113, v236, v113
	v_add_f32_e32 v113, v239, v113
	v_add_f32_e32 v113, v212, v113
	v_add_f32_e32 v113, v215, v113
	v_add_f32_e32 v113, v216, v113
	v_add_f32_e32 v113, v233, v113
	v_add_f32_e32 v113, v234, v113
	v_add_f32_e32 v113, v237, v113
	s_waitcnt lgkmcnt(0)
	v_mfma_f32_32x32x16_bf16 v[96:111], v[242:245], v[146:149], v[96:111]
	v_exp_f32_e32 v242, v114
	v_add_f32_e32 v113, v238, v113
	v_add_f32_e32 v113, v240, v113
	v_add_f32_e32 v113, v112, v113
	v_add_f32_e32 v113, v241, v113
	v_add_f32_e32 v113, v242, v113
	v_exp_f32_e32 v243, v119
	v_add_f32_e32 v113, v115, v113
	v_exp_f32_e32 v119, v120
	v_add_f32_e32 v113, v116, v113
	v_exp_f32_e32 v120, v121
	v_add_f32_e32 v113, v117, v113
	v_exp_f32_e32 v121, v122
	v_add_f32_e32 v113, v118, v113
	v_exp_f32_e32 v122, v123
	v_add_f32_e32 v113, v243, v113
	v_exp_f32_e32 v123, v124
	v_add_f32_e32 v113, v119, v113
	v_exp_f32_e32 v124, v125
	v_add_f32_e32 v113, v120, v113
	v_mfma_f32_32x32x16_bf16 v[128:143], v[246:249], v[146:149], v[128:143]
	v_exp_f32_e32 v125, v126
	v_add_f32_e32 v113, v121, v113
	v_exp_f32_e32 v126, v127
	v_add_f32_e32 v113, v122, v113
	v_add_f32_e32 v113, v123, v113
	v_add_f32_e32 v113, v124, v113
	v_add_f32_e32 v113, v125, v113
	v_add_f32_e32 v113, v126, v113
	v_mov_b32_e32 v114, v113
	s_nop 1
	v_permlane32_swap_b32_e32 v113, v114
	v_cvt_pk_bf16_f32 v250, v211, v213
	v_cvt_pk_bf16_f32 v251, v214, v217
	v_cvt_pk_bf16_f32 v252, v232, v235
	v_cvt_pk_bf16_f32 v253, v236, v239
	v_cvt_pk_bf16_f32 v212, v212, v215
	v_cvt_pk_bf16_f32 v213, v216, v233
	v_cvt_pk_bf16_f32 v214, v234, v237
	v_cvt_pk_bf16_f32 v215, v238, v240
	v_cvt_pk_bf16_f32 v232, v112, v241
	v_cvt_pk_bf16_f32 v233, v242, v115
	v_cvt_pk_bf16_f32 v234, v116, v117
	v_cvt_pk_bf16_f32 v235, v118, v243
	v_cvt_pk_bf16_f32 v116, v119, v120
	v_cvt_pk_bf16_f32 v117, v121, v122
	v_cvt_pk_bf16_f32 v118, v123, v124
	v_cvt_pk_bf16_f32 v119, v125, v126
	v_add_u32_e32 v112, s39, v205
	ds_read_b64_tr_b16 v[120:121], v112 offset:0
	ds_read_b64_tr_b16 v[122:123], v112 offset:0x800
	ds_read_b64_tr_b16 v[124:125], v112 offset:0x1000
	ds_read_b64_tr_b16 v[126:127], v112 offset:0x1800
	ds_read_b64_tr_b16 v[236:237], v112 offset:0x2000
	ds_read_b64_tr_b16 v[238:239], v112 offset:0x2800
	ds_read_b64_tr_b16 v[240:241], v112 offset:0x3000
	ds_read_b64_tr_b16 v[242:243], v112 offset:0x3800
	s_cmp_gt_u32 s44, 60
	s_cselect_b64 s[52:53], -1, 0
	s_and_b64 vcc, exec, s[52:53]
	s_cbranch_vccnz .LBB0_204
	s_add_i32 s10, s56, 0x8000
	s_and_b32 s10, s10, 0x1ffff
	s_add_i32 s12, s21, s10
	v_lshl_add_u64 v[174:175], v[174:175], 0, s[68:69]
	s_add_i32 m0, s12, 0x4000
	s_mov_b64 s[10:11], 0x4040000
	global_load_lds_dwordx4 v[174:175], off
	v_lshl_add_u64 v[174:175], v[172:173], 0, s[10:11]
	s_mov_b32 m0, s12
	s_mov_b64 s[10:11], 0x4040080
	global_load_lds_dwordx4 v[174:175], off
	v_lshl_add_u64 v[174:175], v[176:177], 0, s[68:69]
	s_add_i32 m0, s12, 0x4400
	v_lshl_add_u64 v[172:173], v[172:173], 0, s[10:11]
	global_load_lds_dwordx4 v[174:175], off
	s_add_i32 m0, s12, 0x400
	s_nop 0
	global_load_lds_dwordx4 v[172:173], off
; #define SBAR() __builtin_amdgcn_sched_barrier(0)
; template <int OFF> __device__ __forceinline__ s16x4 tr_read(int vb) { s16x4 r; asm volatile("ds_read_b64_tr_b16 %0, %1 offset:%2" : "=&v"(r) : "v"(vb), "i"(OFF) : "memory"); return r; }
; template <bool FIRST> __device__ __forceinline__ void partialSM(f32x16& p0, f32x16& p1, float& m_reg, f32x16& negm, float& alpha) {
;   float pmax = p0[0];
; #pragma unroll
;   for (int r = 1; r < 16; ++r) pmax = fmaxf(pmax, p0[r]);
; #pragma unroll
;   for (int r = 0; r < 16; ++r) pmax = fmaxf(pmax, p1[r]);
;   { auto rr = __builtin_amdgcn_permlane32_swap(__float_as_uint(pmax), __float_as_uint(pmax), false, false);
;     pmax = fmaxf(__uint_as_float(rr[0]), __uint_as_float(rr[1])); }
;   alpha = 1.f;
;   if (FIRST || __builtin_expect(__any(pmax > THR), 0)) { const float dl = FIRST ? pmax : fmaxf(pmax, 0.f); m_reg += dl; if (!FIRST) alpha = __builtin_amdgcn_exp2f(-dl);
; #pragma unroll
;     for (int r = 0; r < 16; ++r) { p0[r] -= dl; p1[r] -= dl; }
; #pragma unroll
;     for (int r = 0; r < 16; ++r) negm[r] = -m_reg; }
; #pragma unroll
;   for (int r = 0; r < 16; ++r) p0[r] = __builtin_amdgcn_exp2f(p0[r]);
; template <int D0> __device__ __forceinline__ void pv_one(f32x16& od, int vb, bf16x8 pa0, bf16x8 pa1, bf16x8 pa2, bf16x8 pa3) {
;   const s16x4 l0 = tr_read<v_rd_off(D0, 0, 0)>(vb), h0 = tr_read<v_rd_off(D0, 0, 1)>(vb), l1 = tr_read<v_rd_off(D0, 1, 0)>(vb), h1 = tr_read<v_rd_off(D0, 1, 1)>(vb);
;   const s16x4 l2 = tr_read<v_rd_off(D0, 2, 0)>(vb), h2 = tr_read<v_rd_off(D0, 2, 1)>(vb), l3 = tr_read<v_rd_off(D0, 3, 0)>(vb), h3 = tr_read<v_rd_off(D0, 3, 1)>(vb);
;   asm volatile("s_waitcnt lgkmcnt(0)" ::: "memory"); SBAR();
;   od = __builtin_amdgcn_mfma_f32_32x32x16_bf16(pa0, ATT_PK(l0, h0), od, 0, 0, 0);
;   od = __builtin_amdgcn_mfma_f32_32x32x16_bf16(pa1, ATT_PK(l1, h1), od, 0, 0, 0);
;   od = __builtin_amdgcn_mfma_f32_32x32x16_bf16(pa2, ATT_PK(l2, h2), od, 0, 0, 0);
;   od = __builtin_amdgcn_mfma_f32_32x32x16_bf16(pa3, ATT_PK(l3, h3), od, 0, 0, 0);
; }
; __device__ __forceinline__ void pv_d0(f32x16* o, int vb, bf16x8 pa0, bf16x8 pa1, bf16x8 pa2, bf16x8 pa3) {
;   pv_one<0>(o[0], vb, pa0, pa1, pa2, pa3); pv_one<1>(o[1], vb, pa0, pa1, pa2, pa3); pv_one<2>(o[2], vb, pa0, pa1, pa2, pa3); pv_one<3>(o[3], vb, pa0, pa1, pa2, pa3);
; }
.LBB0_204:
	s_waitcnt lgkmcnt(0)
	s_nop 0
	v_mfma_f32_32x32x16_bf16 v[0:15], v[250:253], v[120:123], v[0:15]
	ds_read_b64_tr_b16 v[120:121], v112 offset:0x200
	ds_read_b64_tr_b16 v[122:123], v112 offset:0xa00
	v_mfma_f32_32x32x16_bf16 v[0:15], v[212:215], v[124:127], v[0:15]
	ds_read_b64_tr_b16 v[124:125], v112 offset:0x1200
	ds_read_b64_tr_b16 v[126:127], v112 offset:0x1a00
	v_mfma_f32_32x32x16_bf16 v[0:15], v[232:235], v[236:239], v[0:15]
	ds_read_b64_tr_b16 v[236:237], v112 offset:0x2200
	ds_read_b64_tr_b16 v[238:239], v112 offset:0x2a00
	v_mfma_f32_32x32x16_bf16 v[0:15], v[116:119], v[240:243], v[0:15]
	ds_read_b64_tr_b16 v[240:241], v112 offset:0x3200
	ds_read_b64_tr_b16 v[242:243], v112 offset:0x3a00
	s_waitcnt lgkmcnt(0)
	v_mfma_f32_32x32x16_bf16 v[48:63], v[250:253], v[120:123], v[48:63]
	ds_read_b64_tr_b16 v[120:121], v112 offset:0x400
	ds_read_b64_tr_b16 v[122:123], v112 offset:0xc00
	v_mfma_f32_32x32x16_bf16 v[48:63], v[212:215], v[124:127], v[48:63]
	ds_read_b64_tr_b16 v[124:125], v112 offset:0x1400
	ds_read_b64_tr_b16 v[126:127], v112 offset:0x1c00
	v_mfma_f32_32x32x16_bf16 v[48:63], v[232:235], v[236:239], v[48:63]
	ds_read_b64_tr_b16 v[236:237], v112 offset:0x2400
	ds_read_b64_tr_b16 v[238:239], v112 offset:0x2c00
	v_mfma_f32_32x32x16_bf16 v[48:63], v[116:119], v[240:243], v[48:63]
	ds_read_b64_tr_b16 v[240:241], v112 offset:0x3400
	ds_read_b64_tr_b16 v[242:243], v112 offset:0x3c00
	s_waitcnt lgkmcnt(0)
	v_mfma_f32_32x32x16_bf16 v[32:47], v[250:253], v[120:123], v[32:47]
	ds_read_b64_tr_b16 v[120:121], v112 offset:0x600
	ds_read_b64_tr_b16 v[122:123], v112 offset:0xe00
	v_mfma_f32_32x32x16_bf16 v[32:47], v[212:215], v[124:127], v[32:47]
	ds_read_b64_tr_b16 v[124:125], v112 offset:0x1600
	ds_read_b64_tr_b16 v[126:127], v112 offset:0x1e00
	v_mfma_f32_32x32x16_bf16 v[32:47], v[232:235], v[236:239], v[32:47]
	ds_read_b64_tr_b16 v[236:237], v112 offset:0x2600
	ds_read_b64_tr_b16 v[238:239], v112 offset:0x2e00
	v_mfma_f32_32x32x16_bf16 v[32:47], v[116:119], v[240:243], v[32:47]
	ds_read_b64_tr_b16 v[240:241], v112 offset:0x3600
	ds_read_b64_tr_b16 v[242:243], v112 offset:0x3e00
	s_waitcnt lgkmcnt(0)
	v_mfma_f32_32x32x16_bf16 v[16:31], v[250:253], v[120:123], v[16:31]
	v_exp_f32_e32 v172, v128
	v_exp_f32_e32 v174, v129
	v_exp_f32_e32 v175, v130
	v_exp_f32_e32 v211, v131
	v_max_f32_e32 v112, v129, v129
	v_max_f32_e32 v115, v128, v128
	v_max_f32_e32 v112, v115, v112
	v_max3_f32 v112, v112, v130, v131
	v_max3_f32 v112, v112, v132, v133
	v_max3_f32 v112, v112, v134, v135
	v_max3_f32 v112, v112, v136, v137
	v_mfma_f32_32x32x16_bf16 v[16:31], v[212:215], v[124:127], v[16:31]
	v_exp_f32_e32 v216, v134
	v_exp_f32_e32 v173, v136
	v_exp_f32_e32 v176, v137
	v_exp_f32_e32 v177, v138
	v_exp_f32_e32 v217, v141
	v_max3_f32 v112, v112, v138, v139
	v_max3_f32 v112, v112, v140, v141
	v_max3_f32 v112, v112, v142, v143
	v_max3_f32 v112, v112, v96, v97
	v_max3_f32 v112, v112, v98, v99
	v_max3_f32 v112, v112, v100, v101
	v_max3_f32 v112, v112, v102, v103
	v_mfma_f32_32x32x16_bf16 v[16:31], v[232:235], v[236:239], v[16:31]
	v_exp_f32_e32 v212, v132
	v_exp_f32_e32 v215, v133
	v_exp_f32_e32 v213, v139
	v_exp_f32_e32 v214, v140
	v_max3_f32 v112, v112, v104, v105
	v_max3_f32 v112, v112, v106, v107
	v_max3_f32 v112, v112, v108, v109
	v_max3_f32 v112, v112, v110, v111
	v_mov_b32_e32 v115, v112
	s_nop 1
	v_permlane32_swap_b32_e32 v112, v115
	v_mfma_f32_32x32x16_bf16 v[16:31], v[116:119], v[240:243], v[16:31]
	v_exp_f32_e32 v233, v135
	v_exp_f32_e32 v232, v142
	v_exp_f32_e32 v234, v143
	v_max_f32_e32 v115, v115, v115
	v_max_f32_e32 v112, v112, v112
	v_max_f32_e32 v115, v112, v115
	v_cmp_lt_f32_e32 vcc, s19, v115
	v_mov_b32_e32 v112, 1.0
	s_mov_b32 s98, 0
	s_cbranch_vccnz .LBB0_216
	v_cmp_gt_f32_e32 vcc, 1.0, v112
	s_cbranch_vccz .LBB0_209

; template <bool FIRST> __device__ __forceinline__ void partialSM(f32x16& p0, f32x16& p1, float& m_reg, f32x16& negm, float& alpha) {
;     ...
;   if (FIRST || __builtin_expect(__any(pmax > THR), 0)) { const float dl = FIRST ? pmax : fmaxf(pmax, 0.f); m_reg += dl; if (!FIRST) alpha = __builtin_amdgcn_exp2f(-dl);
; #pragma unroll
;     for (int r = 0; r < 16; ++r) { p0[r] -= dl; p1[r] -= dl; }
; #pragma unroll
;     for (int r = 0; r < 16; ++r) negm[r] = -m_reg; }
; #pragma unroll
;   for (int r = 0; r < 16; ++r) p0[r] = __builtin_amdgcn_exp2f(p0[r]);
; }
; __device__ __forceinline__ void finishSM(f32x16& p0, f32x16& p1, float alpha, float& l_reg, bf16x8& pa0, bf16x8& pa1, bf16x8& pa2, bf16x8& pa3) {
; #pragma unroll
;   for (int r = 0; r < 16; ++r) p1[r] = __builtin_amdgcn_exp2f(p1[r]);
;   float ps = 0;
; #pragma unroll
;   for (int r = 0; r < 16; ++r) ps += p0[r];
; #pragma unroll
;   for (int r = 0; r < 16; ++r) ps += p1[r];
;   { auto rr = __builtin_amdgcn_permlane32_swap(__float_as_uint(ps), __float_as_uint(ps), false, false);
;     ps = __uint_as_float(rr[0]) + __uint_as_float(rr[1]); }
;   l_reg = l_reg * alpha + ps;
.LBB0_213:
	s_cmp_lg_u32 s98, 0
	s_cbranch_scc0 .Lexp2_done
	v_exp_f32_e32 v172, v128
	v_exp_f32_e32 v174, v129
	v_exp_f32_e32 v175, v130
	v_exp_f32_e32 v211, v131
	v_exp_f32_e32 v212, v132
	v_exp_f32_e32 v215, v133
	v_exp_f32_e32 v216, v134
	v_exp_f32_e32 v233, v135
	v_exp_f32_e32 v173, v136
	v_exp_f32_e32 v176, v137
	v_exp_f32_e32 v177, v138
	v_exp_f32_e32 v213, v139
	v_exp_f32_e32 v214, v140
	v_exp_f32_e32 v217, v141
	v_exp_f32_e32 v232, v142
	v_exp_f32_e32 v234, v143
.Lexp2_done:
	v_add_f32_e32 v115, v208, v209
	s_add_i32 s44, s44, 2
	s_barrier
	s_xor_b32 s39, s39, 0x10000
	s_xor_b32 s56, s56, 0x10000
	v_fmac_f32_e32 v115, v207, v180
	v_add_f32_e32 v180, v113, v114
	s_add_u32 s50, s50, 0x20000
	v_fmac_f32_e32 v180, v115, v210
	s_addc_u32 s51, s51, 0
	s_and_b64 vcc, exec, s[52:53]
	s_cbranch_vccnz .LBB0_217
	v_mov_b32_e32 v207, v112
	s_branch .LBB0_197
.LBB0_215:
	s_mov_b32 s98, 1
	v_max_f32_e32 v64, v96, v96
	v_max_f32_e32 v64, 0, v64
	v_exp_f32_e64 v210, -v64
	v_add_f32_e32 v206, v206, v64
	v_pk_add_f32 v[128:129], v[128:129], v[64:65] op_sel_hi:[1,0] neg_lo:[0,1] neg_hi:[0,1]
	v_pk_add_f32 v[130:131], v[130:131], v[64:65] op_sel_hi:[1,0] neg_lo:[0,1] neg_hi:[0,1]
	v_pk_add_f32 v[132:133], v[132:133], v[64:65] op_sel_hi:[1,0] neg_lo:[0,1] neg_hi:[0,1]
	v_pk_add_f32 v[134:135], v[134:135], v[64:65] op_sel_hi:[1,0] neg_lo:[0,1] neg_hi:[0,1]
	v_pk_add_f32 v[136:137], v[136:137], v[64:65] op_sel_hi:[1,0] neg_lo:[0,1] neg_hi:[0,1]
	v_pk_add_f32 v[138:139], v[138:139], v[64:65] op_sel_hi:[1,0] neg_lo:[0,1] neg_hi:[0,1]
	v_pk_add_f32 v[140:141], v[140:141], v[64:65] op_sel_hi:[1,0] neg_lo:[0,1] neg_hi:[0,1]
	v_pk_add_f32 v[142:143], v[142:143], v[64:65] op_sel_hi:[1,0] neg_lo:[0,1] neg_hi:[0,1]
	v_sub_f32_e32 v127, v127, v64
	v_sub_f32_e32 v126, v126, v64
	v_sub_f32_e32 v125, v125, v64
	v_sub_f32_e32 v124, v124, v64
	v_sub_f32_e32 v123, v123, v64
	v_sub_f32_e32 v122, v122, v64
	v_sub_f32_e32 v121, v121, v64
	v_sub_f32_e32 v120, v120, v64
	v_sub_f32_e32 v119, v119, v64
	v_sub_f32_e32 v118, v118, v64
	v_sub_f32_e32 v117, v117, v64
	v_sub_f32_e32 v116, v116, v64
	v_sub_f32_e32 v115, v115, v64
	v_sub_f32_e32 v114, v114, v64
	v_sub_f32_e32 v113, v113, v64
	v_sub_f32_e32 v112, v112, v64
	v_xor_b32_e32 v64, 0x80000000, v206
	v_mov_b32_e32 v65, v64
	v_mov_b32_e32 v66, v64
	v_mov_b32_e32 v67, v64
	v_mov_b32_e32 v68, v64
	v_mov_b32_e32 v69, v64
	v_mov_b32_e32 v70, v64
	v_mov_b32_e32 v71, v64
	v_mov_b32_e32 v72, v64
	v_mov_b32_e32 v73, v64
	v_mov_b32_e32 v74, v64
	v_mov_b32_e32 v75, v64
	v_mov_b32_e32 v76, v64
	v_mov_b32_e32 v77, v64
	v_mov_b32_e32 v78, v64
	v_mov_b32_e32 v79, v64
	v_mov_b32_e32 v80, v64
	v_mov_b32_e32 v81, v64
	v_mov_b32_e32 v82, v64
	v_mov_b32_e32 v83, v64
	v_mov_b32_e32 v84, v64
	v_mov_b32_e32 v85, v64
	v_mov_b32_e32 v86, v64
	v_mov_b32_e32 v87, v64
	v_mov_b32_e32 v88, v64
	v_mov_b32_e32 v89, v64
	v_mov_b32_e32 v90, v64
	v_mov_b32_e32 v91, v64
	v_mov_b32_e32 v92, v64
	v_mov_b32_e32 v93, v64
	v_mov_b32_e32 v94, v64
	v_mov_b32_e32 v95, v64
	v_cmp_gt_f32_e32 vcc, 1.0, v210
	s_cbranch_vccnz .LBB0_199
	s_branch .LBB0_202
.LBB0_216:
	s_mov_b32 s98, 1
	v_max_f32_e32 v64, v115, v115
	v_max_f32_e32 v64, 0, v64
	v_exp_f32_e64 v112, -v64
	v_add_f32_e32 v206, v206, v64
	v_pk_add_f32 v[128:129], v[128:129], v[64:65] op_sel_hi:[1,0] neg_lo:[0,1] neg_hi:[0,1]
	v_pk_add_f32 v[130:131], v[130:131], v[64:65] op_sel_hi:[1,0] neg_lo:[0,1] neg_hi:[0,1]
	v_pk_add_f32 v[132:133], v[132:133], v[64:65] op_sel_hi:[1,0] neg_lo:[0,1] neg_hi:[0,1]
	v_pk_add_f32 v[134:135], v[134:135], v[64:65] op_sel_hi:[1,0] neg_lo:[0,1] neg_hi:[0,1]
	v_pk_add_f32 v[136:137], v[136:137], v[64:65] op_sel_hi:[1,0] neg_lo:[0,1] neg_hi:[0,1]
	v_pk_add_f32 v[138:139], v[138:139], v[64:65] op_sel_hi:[1,0] neg_lo:[0,1] neg_hi:[0,1]
	v_pk_add_f32 v[140:141], v[140:141], v[64:65] op_sel_hi:[1,0] neg_lo:[0,1] neg_hi:[0,1]
	v_pk_add_f32 v[142:143], v[142:143], v[64:65] op_sel_hi:[1,0] neg_lo:[0,1] neg_hi:[0,1]
	v_sub_f32_e32 v111, v111, v64
	v_sub_f32_e32 v110, v110, v64
	v_sub_f32_e32 v109, v109, v64
	v_sub_f32_e32 v108, v108, v64
	v_sub_f32_e32 v107, v107, v64
	v_sub_f32_e32 v106, v106, v64
	v_sub_f32_e32 v105, v105, v64
	v_sub_f32_e32 v104, v104, v64
	v_sub_f32_e32 v103, v103, v64
	v_sub_f32_e32 v102, v102, v64
	v_sub_f32_e32 v101, v101, v64
	v_sub_f32_e32 v100, v100, v64
	v_sub_f32_e32 v99, v99, v64
	v_sub_f32_e32 v98, v98, v64
	v_sub_f32_e32 v97, v97, v64
	v_sub_f32_e32 v96, v96, v64
	v_xor_b32_e32 v64, 0x80000000, v206
	v_mov_b32_e32 v65, v64
	v_mov_b32_e32 v66, v64
	v_mov_b32_e32 v67, v64
	v_mov_b32_e32 v68, v64
	v_mov_b32_e32 v69, v64
	v_mov_b32_e32 v70, v64
	v_mov_b32_e32 v71, v64
	v_mov_b32_e32 v72, v64
	v_mov_b32_e32 v73, v64
	v_mov_b32_e32 v74, v64
	v_mov_b32_e32 v75, v64
	v_mov_b32_e32 v76, v64
	v_mov_b32_e32 v77, v64
	v_mov_b32_e32 v78, v64
	v_mov_b32_e32 v79, v64
	v_mov_b32_e32 v80, v64
	v_mov_b32_e32 v81, v64
	v_mov_b32_e32 v82, v64
	v_mov_b32_e32 v83, v64
	v_mov_b32_e32 v84, v64
	v_mov_b32_e32 v85, v64
	v_mov_b32_e32 v86, v64
	v_mov_b32_e32 v87, v64
	v_mov_b32_e32 v88, v64
	v_mov_b32_e32 v89, v64
	v_mov_b32_e32 v90, v64
	v_mov_b32_e32 v91, v64
	v_mov_b32_e32 v92, v64
	v_mov_b32_e32 v93, v64
	v_mov_b32_e32 v94, v64
	v_mov_b32_e32 v95, v64
	v_cmp_gt_f32_e32 vcc, 1.0, v112
	s_cbranch_vccnz .LBB0_206
	s_branch .LBB0_209

; __global__ void __launch_bounds__(512, 2) mega(Args a) {
;     extern __shared__ __attribute__((aligned(16))) unsigned char lds[];
	.amdhsa_kernel _Z4mega4Args
		.amdhsa_group_segment_fixed_size 0
		.amdhsa_private_segment_fixed_size 0
		.amdhsa_kernarg_size 384
		.amdhsa_user_sgpr_count 2
		.amdhsa_user_sgpr_dispatch_ptr 0
		.amdhsa_user_sgpr_queue_ptr 0
		.amdhsa_user_sgpr_kernarg_segment_ptr 1
		.amdhsa_user_sgpr_dispatch_id 0
		.amdhsa_user_sgpr_kernarg_preload_length 0
		.amdhsa_user_sgpr_kernarg_preload_offset 0
		.amdhsa_user_sgpr_private_segment_size 0
		.amdhsa_uses_dynamic_stack 0
		.amdhsa_enable_private_segment 0
		.amdhsa_system_sgpr_workgroup_id_x 1
		.amdhsa_system_sgpr_workgroup_id_y 0
		.amdhsa_system_sgpr_workgroup_id_z 0
		.amdhsa_system_sgpr_workgroup_info 0
		.amdhsa_system_vgpr_workitem_id 2
		.amdhsa_next_free_vgpr 256
		.amdhsa_next_free_sgpr 99
		.amdhsa_accum_offset 256
		.amdhsa_reserve_vcc 1
		.amdhsa_float_round_mode_32 0
		.amdhsa_float_round_mode_16_64 0
		.amdhsa_float_denorm_mode_32 3
		.amdhsa_float_denorm_mode_16_64 3
		.amdhsa_dx10_clamp 1
		.amdhsa_ieee_mode 1
		.amdhsa_fp16_overflow 0
		.amdhsa_tg_split 0
		.amdhsa_exception_fp_ieee_invalid_op 0
		.amdhsa_exception_fp_denorm_src 0
		.amdhsa_exception_fp_ieee_div_zero 0
		.amdhsa_exception_fp_ieee_overflow 0
		.amdhsa_exception_fp_ieee_underflow 0
		.amdhsa_exception_fp_ieee_inexact 0
		.amdhsa_exception_int_div_zero 0
	.end_amdhsa_kernel

; __global__ void __launch_bounds__(512, 2) mega(Args a) {
;     extern __shared__ __attribute__((aligned(16))) unsigned char lds[];
amdhsa.kernels:
  - .agpr_count:     0
    .args:
      - .offset:         0
        .size:           128
        .value_kind:     by_value
      - .offset:         128
        .size:           4
        .value_kind:     hidden_block_count_x
      - .offset:         132
        .size:           4
        .value_kind:     hidden_block_count_y
      - .offset:         136
        .size:           4
        .value_kind:     hidden_block_count_z
      - .offset:         140
        .size:           2
        .value_kind:     hidden_group_size_x
      - .offset:         142
        .size:           2
        .value_kind:     hidden_group_size_y
      - .offset:         144
        .size:           2
        .value_kind:     hidden_group_size_z
      - .offset:         146
        .size:           2
        .value_kind:     hidden_remainder_x
      - .offset:         148
        .size:           2
        .value_kind:     hidden_remainder_y
      - .offset:         150
        .size:           2
        .value_kind:     hidden_remainder_z
      - .offset:         168
        .size:           8
        .value_kind:     hidden_global_offset_x
      - .offset:         176
        .size:           8
        .value_kind:     hidden_global_offset_y
      - .offset:         184
        .size:           8
        .value_kind:     hidden_global_offset_z
      - .offset:         192
        .size:           2
        .value_kind:     hidden_grid_dims
      - .offset:         216
        .size:           8
        .value_kind:     hidden_multigrid_sync_arg
      - .offset:         248
        .size:           4
        .value_kind:     hidden_dynamic_lds_size
    .group_segment_fixed_size: 0
    .kernarg_segment_align: 8
    .kernarg_segment_size: 384
    .language:       OpenCL C
    .language_version:
      - 2
      - 0
    .max_flat_workgroup_size: 512
    .name:           _Z4mega4Args
    .private_segment_fixed_size: 0
    .sgpr_count:     105
    .sgpr_spill_count: 107
    .symbol:         _Z4mega4Args.kd
    .uniform_work_group_size: 1
    .uses_dynamic_stack: false
    .vgpr_count:     256
    .vgpr_spill_count: 0
    .wavefront_size: 64
